# half-tile start stagger (7x s_sleep 127, ~24us) for WGs >= 256 at the start of GEMM phases 1,5,10,14 to de-phase the two WGs per CU, on top of v_p11dyn
# speedup vs baseline: 1.0003x; 1.0003x over previous
.LBB0_203:
	s_or_b64 exec, exec, s[0:1]
	s_cmpk_lt_i32 s2, 0x1000
	s_cselect_b64 s[18:19], -1, 0
	s_cmpk_gt_i32 s2, 0xfff
	s_waitcnt lgkmcnt(0)
	s_barrier
	s_cbranch_scc1 .LBB0_276
	s_add_u32 s3, s72, 0x3000000
	s_addc_u32 s34, s73, 0
	s_add_u32 s8, s72, 0x7000000
	s_addc_u32 s9, s73, 0
	s_add_u32 s12, s72, 0x13200000
	s_addc_u32 s13, s73, 0
	s_add_u32 s14, s72, 0x7200000
	s_addc_u32 s15, s73, 0
	s_add_u32 s16, s72, 0xb200000
	s_addc_u32 s17, s73, 0
	s_add_u32 s20, s72, 0xf200000
	s_addc_u32 s21, s73, 0
	v_mov_b32_e32 v153, 0
	s_mov_b64 s[22:23], 0x20000
	s_mov_b32 s35, 0x20000
	s_mov_b64 s[24:25], 0x40000
	s_mov_b32 s36, 0x40000
	s_mov_b64 s[28:29], 0x60000
	s_mov_b32 s37, 0x60000
	s_mov_b32 s31, 0
	s_movk_i32 s38, 0x7f
	s_movk_i32 s39, 0x4c
	s_movk_i32 s40, 0x5c
	s_movk_i32 s41, 0x6c
	s_movk_i32 s42, 0x7c
	s_mov_b32 s43, 0xc2fc0000
	s_mov_b32 s44, 0x3f2aaaab
	s_mov_b32 s45, 0x3f317218
	s_mov_b32 s46, 0x33800000
	s_movk_i32 s47, 0x7fff
	s_movk_i32 s48, 0x7e
	s_movk_i32 s49, 0x7d
	s_movk_i32 s50, 0x7f00
	s_movk_i32 s51, 0x3f9c
	s_movk_i32 s56, 0x3fac
	s_movk_i32 s57, 0x3fbc
	s_movk_i32 s58, 0x3fcc
	s_movk_i32 s59, 0x3fdc
	s_movk_i32 s62, 0x3fec
	s_movk_i32 s63, 0x3ffc
	v_mov_b32_e32 v166, 0x50
	v_mov_b32_e32 v167, 0x60
	v_mov_b32_e32 v168, 0x70
	v_mov_b32_e32 v169, 0x42800000
	v_not_b32_e32 v170, 63
	v_mov_b32_e32 v171, 0x4c
	v_mov_b32_e32 v172, 0x5c
	v_mov_b32_e32 v173, 0x6c
	v_mov_b32_e32 v174, 0x7c
	s_mov_b32 s64, s2
	s_cmpk_lt_u32 s2, 0x100
	s_cbranch_scc1 .Lbig_stag_0
	s_sleep 127
	s_sleep 127
	s_sleep 127
	s_sleep 127
	s_sleep 127
	s_sleep 127
	s_sleep 127
.Lbig_stag_0:
	s_branch .LBB0_207
.LBB0_205:
.LBB0_206:
	s_add_i32 s64, s64, s74
	s_cmpk_lt_i32 s64, 0x1000
	s_cbranch_scc0 .LBB0_276

.LBB0_500:
	s_or_b64 exec, exec, s[0:1]
	s_cmpk_lt_i32 s2, 0x800
	s_cselect_b64 s[0:1], -1, 0
	s_cmpk_gt_i32 s2, 0x7ff
	s_waitcnt lgkmcnt(0)
	s_barrier
	s_cbranch_scc1 .LBB0_505
	s_add_u32 s3, s72, 0x3000000
	s_addc_u32 s4, s73, 0
	s_add_u32 s6, s72, 0x7000000
	s_addc_u32 s7, s73, 0
	s_add_u32 s8, s72, 0x7200000
	s_addc_u32 s9, s73, 0
	s_add_u32 s5, s72, 0x7100000
	s_addc_u32 s26, s73, 0
	s_mov_b32 s15, 0
	s_waitcnt vmcnt(9)
	v_mov_b32_e32 v153, 0
	s_mov_b64 s[16:17], 0x20000
	s_mov_b32 s27, 0x20000
	s_mov_b64 s[22:23], 0x40000
	s_mov_b32 s30, 0x40000
	s_mov_b64 s[24:25], 0x60000
	s_mov_b32 s31, 0x60000
	v_mov_b32_e32 v194, 0x4000
	s_mov_b32 s34, s2
	s_cmpk_lt_u32 s2, 0x100
	s_cbranch_scc1 .Lbig_stag_2
	s_sleep 127
	s_sleep 127
	s_sleep 127
	s_sleep 127
	s_sleep 127
	s_sleep 127
	s_sleep 127
.Lbig_stag_2:
.LBB0_502:
	s_ashr_i32 s14, s34, 3
	s_lshr_b32 s28, s14, 28
	s_add_i32 s28, s14, s28
	s_and_b32 s29, s28, -16
	s_sub_i32 s33, s14, s29
	s_lshl_b32 s14, s28, 7
	s_lshl_b32 s28, s34, 8
	s_and_b32 s14, s14, 0xfffff800
	s_and_b32 s28, s28, 0x700
	s_or_b32 s28, s14, s28
	s_ashr_i32 s29, s28, 31
	s_lshl_b32 s35, s33, 7
	s_lshl_b64 s[36:37], s[28:29], 11
	s_add_u32 s36, s3, s36
	s_addc_u32 s37, s4, s37
	s_add_i32 s14, s35, 0x1000
	v_mov_b32_e32 v36, v220
	s_lshl_b64 s[38:39], s[14:15], 11
	s_add_u32 s38, s72, s38
	v_ashrrev_i32_e32 v26, 2, v36
	v_ashrrev_i32_e32 v27, 31, v26
	s_addc_u32 s39, s73, s39
	v_lshlrev_b64 v[0:1], 11, v[26:27]
	v_lshlrev_b32_e32 v4, 4, v36
	v_lshl_add_u64 v[2:3], s[38:39], 0, v[0:1]
	v_lshl_add_u64 v[0:1], s[36:37], 0, v[0:1]
	v_and_b32_e32 v152, 48, v4
	v_lshl_add_u64 v[154:155], v[0:1], 0, v[152:153]
	v_add_co_u32_e32 v28, vcc, s27, v154
	v_lshl_add_u64 v[156:157], v[2:3], 0, v[152:153]
	s_nop 0
	v_addc_co_u32_e32 v29, vcc, 0, v155, vcc
	v_add_co_u32_e32 v30, vcc, s30, v154
	global_load_dwordx4 v[2:5], v[154:155], off
	s_nop 0
	v_addc_co_u32_e32 v31, vcc, 0, v155, vcc
	v_add_co_u32_e32 v32, vcc, s31, v154
	global_load_dwordx4 v[6:9], v[28:29], off
	s_nop 0
	v_addc_co_u32_e32 v33, vcc, 0, v155, vcc
	v_add_co_u32_e32 v34, vcc, s27, v156
	global_load_dwordx4 v[10:13], v[30:31], off
	s_nop 0
	v_addc_co_u32_e32 v35, vcc, 0, v157, vcc
	global_load_dwordx4 v[14:17], v[32:33], off
	global_load_dwordx4 v[18:21], v[156:157], off
	global_load_dwordx4 v[22:25], v[34:35], off
	global_load_dwordx4 v[44:47], v[154:155], off offset:64
	global_load_dwordx4 v[60:63], v[28:29], off offset:64
	global_load_dwordx4 v[68:71], v[30:31], off offset:64
	global_load_dwordx4 v[140:143], v[32:33], off offset:64
	global_load_dwordx4 v[52:55], v[156:157], off offset:64
	global_load_dwordx4 v[144:147], v[34:35], off offset:64
	v_lshrrev_b32_e32 v27, 4, v36
	v_lshrrev_b32_e32 v37, 2, v36
	v_sub_u32_e32 v40, 0, v27
	v_sub_u32_e32 v37, 0, v37
	v_and_b32_e32 v38, 0x3ffff8f, v36
	v_lshlrev_b32_e32 v39, 6, v36
	v_xor_b32_e32 v36, v36, v40
	v_xor_b32_e32 v27, v27, v37
	v_lshlrev_b32_e32 v36, 4, v36
	v_lshlrev_b32_e32 v27, 4, v27
	v_and_b32_e32 v41, 0x1000, v39
	v_and_b32_e32 v36, 48, v36
	v_and_b32_e32 v27, 48, v27
	v_and_b32_e32 v42, 0x3c0, v39
	v_and_b32_e32 v39, 0xffffe3c0, v39
	v_lshl_add_u32 v38, v38, 6, v194
	v_lshl_or_b32 v152, v26, 6, v36
	v_or_b32_e32 v26, v27, v41
	s_mov_b32 s29, -2
	s_mov_b32 s36, s15
	v_mov_b32_e32 v0, 0
	v_mov_b32_e32 v1, v153
	v_or3_b32 v166, v41, v42, v27
	v_add_u32_e32 v167, v27, v39
	v_add_u32_e32 v168, v27, v38
	v_add_u32_e32 v169, v26, v42
	v_lshl_add_u64 v[158:159], v[154:155], 0, s[16:17]
	v_lshl_add_u64 v[160:161], v[154:155], 0, s[22:23]
	v_lshl_add_u64 v[162:163], v[154:155], 0, s[24:25]
	v_lshl_add_u64 v[164:165], v[156:157], 0, s[16:17]
	v_mov_b32_e32 v26, v153
	v_mov_b32_e32 v27, v153
	v_mov_b32_e32 v28, 0
	v_mov_b32_e32 v29, v153
	v_mov_b32_e32 v30, v153
	v_mov_b32_e32 v31, v153
	v_mov_b32_e32 v32, 0
	v_mov_b32_e32 v33, v153
	v_mov_b32_e32 v34, v153
	v_mov_b32_e32 v35, v153
	v_mov_b32_e32 v36, 0
	v_mov_b32_e32 v37, v153
	v_mov_b32_e32 v38, v153
	v_mov_b32_e32 v39, v153
	v_mov_b32_e32 v40, 0
	v_mov_b32_e32 v41, v153
	v_mov_b32_e32 v42, v153
	v_mov_b32_e32 v43, v153
	v_mov_b32_e32 v48, 0
	s_waitcnt vmcnt(11)
	ds_write_b128 v152, v[2:5]
	s_waitcnt vmcnt(10)
	ds_write_b128 v152, v[6:9] offset:4096
	s_waitcnt vmcnt(9)
	ds_write_b128 v152, v[10:13] offset:8192
	s_waitcnt vmcnt(8)
	ds_write_b128 v152, v[14:17] offset:12288
	s_waitcnt vmcnt(7)
	ds_write_b128 v152, v[18:21] offset:32768
	s_waitcnt vmcnt(6)
	ds_write_b128 v152, v[22:25] offset:36864
	v_mov_b32_e32 v2, v153
	v_mov_b32_e32 v3, v153
	v_mov_b32_e32 v4, 0
	v_mov_b32_e32 v5, v153
	v_mov_b32_e32 v6, v153
	v_mov_b32_e32 v7, v153
	v_mov_b32_e32 v8, 0
	v_mov_b32_e32 v9, v153
	v_mov_b32_e32 v10, v153
	v_mov_b32_e32 v11, v153
	v_mov_b32_e32 v12, 0
	v_mov_b32_e32 v13, v153
	v_mov_b32_e32 v14, v153
	v_mov_b32_e32 v15, v153
	v_mov_b32_e32 v16, 0
	v_mov_b32_e32 v17, v153
	v_mov_b32_e32 v18, v153
	v_mov_b32_e32 v19, v153
	v_mov_b32_e32 v20, 0
	v_mov_b32_e32 v21, v153
	v_mov_b32_e32 v22, v153
	v_mov_b32_e32 v23, v153
	v_mov_b32_e32 v24, 0
	v_mov_b32_e32 v25, v153
	v_mov_b32_e32 v49, v153
	v_mov_b32_e32 v50, v153
	v_mov_b32_e32 v51, v153
	v_mov_b32_e32 v56, 0
	v_mov_b32_e32 v57, v153
	v_mov_b32_e32 v58, v153
	v_mov_b32_e32 v59, v153
	v_mov_b32_e32 v64, 0
	v_mov_b32_e32 v65, v153
	v_mov_b32_e32 v66, v153
	v_mov_b32_e32 v67, v153
	v_mov_b32_e32 v72, 0
	v_mov_b32_e32 v73, v153
	v_mov_b32_e32 v74, v153
	v_mov_b32_e32 v75, v153
	v_mov_b32_e32 v76, 0
	v_mov_b32_e32 v77, v153
	v_mov_b32_e32 v78, v153
	v_mov_b32_e32 v79, v153
	v_mov_b32_e32 v80, 0
	v_mov_b32_e32 v81, v153
	v_mov_b32_e32 v82, v153
	v_mov_b32_e32 v83, v153
	v_mov_b32_e32 v84, 0
	v_mov_b32_e32 v85, v153
	v_mov_b32_e32 v86, v153
	v_mov_b32_e32 v87, v153
	v_mov_b32_e32 v88, 0
	v_mov_b32_e32 v89, v153
	v_mov_b32_e32 v90, v153
	v_mov_b32_e32 v91, v153
	v_mov_b32_e32 v92, 0
	v_mov_b32_e32 v93, v153
	v_mov_b32_e32 v94, v153
	v_mov_b32_e32 v95, v153
	v_mov_b32_e32 v96, 0
	v_mov_b32_e32 v97, v153
	v_mov_b32_e32 v98, v153
	v_mov_b32_e32 v99, v153
	v_mov_b32_e32 v100, 0
	v_mov_b32_e32 v101, v153
	v_mov_b32_e32 v102, v153
	v_mov_b32_e32 v103, v153
	v_mov_b32_e32 v104, 0
	v_mov_b32_e32 v105, v153
	v_mov_b32_e32 v106, v153
	v_mov_b32_e32 v107, v153
	v_mov_b32_e32 v108, 0
	v_mov_b32_e32 v109, v153
	v_mov_b32_e32 v110, v153
	v_mov_b32_e32 v111, v153
	v_mov_b32_e32 v112, 0
	v_mov_b32_e32 v113, v153
	v_mov_b32_e32 v114, v153
	v_mov_b32_e32 v115, v153
	v_mov_b32_e32 v116, 0
	v_mov_b32_e32 v117, v153
	v_mov_b32_e32 v118, v153
	v_mov_b32_e32 v119, v153
	v_mov_b32_e32 v120, 0
	v_mov_b32_e32 v121, v153
	v_mov_b32_e32 v122, v153
	v_mov_b32_e32 v123, v153
	v_mov_b32_e32 v124, 0
	v_mov_b32_e32 v125, v153
	v_mov_b32_e32 v126, v153
	v_mov_b32_e32 v127, v153
	v_mov_b32_e32 v128, 0
	v_mov_b32_e32 v129, v153
	v_mov_b32_e32 v130, v153
	v_mov_b32_e32 v131, v153
	v_mov_b32_e32 v132, 0
	v_mov_b32_e32 v133, v153
	v_mov_b32_e32 v134, v153
	v_mov_b32_e32 v135, v153
	v_mov_b32_e32 v136, 0
	v_mov_b32_e32 v137, v153
	v_mov_b32_e32 v138, v153
	v_mov_b32_e32 v139, v153
	v_mov_b32_e32 v148, 0
	v_mov_b32_e32 v149, v153
	v_mov_b32_e32 v150, v153
	v_mov_b32_e32 v151, v153
	s_waitcnt lgkmcnt(0)
	s_add_i32 s37, s36, 64
	s_min_u32 s14, s37, 0x3e0
	s_lshl_b32 s14, s14, 1
	v_lshl_add_u64 v[170:171], v[154:155], 0, s[14:15]
	v_lshl_add_u64 v[174:175], v[158:159], 0, s[14:15]
	v_lshl_add_u64 v[178:179], v[160:161], 0, s[14:15]
	v_lshl_add_u64 v[182:183], v[162:163], 0, s[14:15]
	v_lshl_add_u64 v[186:187], v[156:157], 0, s[14:15]
	v_lshl_add_u64 v[190:191], v[164:165], 0, s[14:15]

.LBB0_697:
	s_or_b64 exec, exec, s[0:1]
	s_cmpk_gt_i32 s2, 0xbff
	s_waitcnt lgkmcnt(0)
	s_barrier
	s_cbranch_scc1 .LBB0_712
	s_add_u32 s14, s72, 0x7040000
	s_addc_u32 s15, s73, 0
	s_add_u32 s3, s72, 0x7200000
	s_addc_u32 s4, s73, 0
	s_add_u32 s5, s72, 0x1b200000
	s_addc_u32 s6, s73, 0
	s_add_u32 s7, s72, 0x1000000
	s_addc_u32 s8, s73, 0
	s_mov_b32 s17, 0
	s_waitcnt vmcnt(9)
	v_mov_b32_e32 v153, 0
	s_mov_b64 s[22:23], 0x20000
	s_mov_b32 s9, 0x20000
	s_mov_b64 s[24:25], 0x40000
	s_mov_b32 s31, 0x40000
	s_mov_b64 s[28:29], 0x60000
	s_mov_b32 s35, 0x60000
	v_mov_b32_e32 v166, 0x358637bd
	s_mov_b32 s30, 0x3a800000
	s_mov_b32 s40, 0x800000
	s_movk_i32 s41, 0x3f8f
	s_movk_i32 s42, 0x3f9f
	s_movk_i32 s43, 0x3faf
	s_movk_i32 s44, 0x3fbf
	s_movk_i32 s45, 0x3fcf
	s_movk_i32 s46, 0x3fdf
	s_movk_i32 s47, 0x3fef
	s_movk_i32 s48, 0x3fff
	s_mov_b32 s34, 0x358637bd
	s_movk_i32 s49, 0xfe
	s_mov_b64 s[36:37], 0x60
	s_movk_i32 s50, 0xff
	v_mov_b32_e32 v167, 0x4000
	s_mov_b32 s51, s2
	s_cmpk_lt_u32 s2, 0x100
	s_cbranch_scc1 .Lbig_stag_1
	s_sleep 127
	s_sleep 127
	s_sleep 127
	s_sleep 127
	s_sleep 127
	s_sleep 127
	s_sleep 127
.Lbig_stag_1:
	s_branch .LBB0_700
.LBB0_699:
	s_add_i32 s51, s51, s74
	s_cmpk_lt_i32 s51, 0xc00
	s_cbranch_scc0 .LBB0_712

.LBB0_1734:
	s_or_b64 exec, exec, s[0:1]
	v_readlane_b32 s0, v254, 30
	v_readlane_b32 s1, v254, 31
	s_and_b64 vcc, exec, s[0:1]
	s_waitcnt lgkmcnt(0)
	s_barrier
	s_cbranch_vccnz .LBB0_1739
	s_add_u32 s3, s72, 0x1b200000
	s_addc_u32 s4, s73, 0
	s_add_u32 s5, s72, 0x1a20000
	s_addc_u32 s6, s73, 0
	s_add_u32 s0, s72, 0x7040000
	s_addc_u32 s1, s73, 0
	s_add_u32 s10, s72, 0x13200000
	s_addc_u32 s11, s73, 0
	s_mov_b32 s13, 0
	s_waitcnt vmcnt(9)
	v_mov_b32_e32 v153, 0
	s_mov_b64 s[14:15], 0x20000
	s_mov_b32 s7, 0x20000
	s_mov_b64 s[16:17], 0x40000
	s_mov_b32 s8, 0x40000
	s_mov_b64 s[18:19], 0x60000
	s_mov_b32 s9, 0x60000
	v_mov_b32_e32 v166, 0x4000
	v_mov_b32_e32 v167, 0x358637bd
	s_mov_b32 s22, 0x800000
	s_mov_b32 s23, s2
	s_cmpk_lt_u32 s2, 0x100
	s_cbranch_scc1 .Lbig_stag_3
	s_sleep 127
	s_sleep 127
	s_sleep 127
	s_sleep 127
	s_sleep 127
	s_sleep 127
	s_sleep 127
.Lbig_stag_3:
.LBB0_1736:
	s_ashr_i32 s12, s23, 3
	s_lshr_b32 s20, s12, 28
	s_add_i32 s20, s12, s20
	s_and_b32 s21, s20, 0x1fffff0
	s_sub_i32 s12, s12, s21
	s_lshl_b32 s20, s20, 7
	s_lshl_b32 s21, s23, 8
	s_and_b32 s20, s20, 0xfffff800
	s_and_b32 s21, s21, 0x700
	s_or_b32 s20, s20, s21
	s_ashr_i32 s21, s20, 31
	s_lshl_b32 s24, s12, 7
	s_lshl_b64 s[26:27], s[20:21], 11
	s_add_u32 s26, s3, s26
	s_addc_u32 s27, s4, s27
	s_add_i32 s12, s24, 0x880
	v_mov_b32_e32 v36, v220
	s_lshl_b64 s[28:29], s[12:13], 11
	s_add_u32 s28, s5, s28
	v_ashrrev_i32_e32 v26, 2, v36
	v_ashrrev_i32_e32 v27, 31, v26
	s_addc_u32 s29, s6, s29
	v_lshlrev_b64 v[0:1], 11, v[26:27]
	v_lshlrev_b32_e32 v4, 4, v36
	v_lshl_add_u64 v[2:3], s[28:29], 0, v[0:1]
	v_lshl_add_u64 v[0:1], s[26:27], 0, v[0:1]
	v_and_b32_e32 v152, 48, v4
	v_lshl_add_u64 v[154:155], v[0:1], 0, v[152:153]
	v_add_co_u32_e32 v28, vcc, s7, v154
	v_lshl_add_u64 v[156:157], v[2:3], 0, v[152:153]
	s_nop 0
	v_addc_co_u32_e32 v29, vcc, 0, v155, vcc
	v_add_co_u32_e32 v30, vcc, s8, v154
	global_load_dwordx4 v[2:5], v[154:155], off
	s_nop 0
	v_addc_co_u32_e32 v31, vcc, 0, v155, vcc
	v_add_co_u32_e32 v32, vcc, s9, v154
	global_load_dwordx4 v[6:9], v[28:29], off
	s_nop 0
	v_addc_co_u32_e32 v33, vcc, 0, v155, vcc
	v_add_co_u32_e32 v34, vcc, s7, v156
	global_load_dwordx4 v[10:13], v[30:31], off
	s_nop 0
	v_addc_co_u32_e32 v35, vcc, 0, v157, vcc
	global_load_dwordx4 v[14:17], v[32:33], off
	global_load_dwordx4 v[18:21], v[156:157], off
	global_load_dwordx4 v[22:25], v[34:35], off
	global_load_dwordx4 v[120:123], v[154:155], off offset:64
	global_load_dwordx4 v[124:127], v[28:29], off offset:64
	global_load_dwordx4 v[128:131], v[30:31], off offset:64
	global_load_dwordx4 v[136:139], v[32:33], off offset:64
	global_load_dwordx4 v[132:135], v[156:157], off offset:64
	global_load_dwordx4 v[140:143], v[34:35], off offset:64
	v_lshrrev_b32_e32 v27, 4, v36
	v_lshrrev_b32_e32 v37, 2, v36
	v_sub_u32_e32 v40, 0, v27
	v_sub_u32_e32 v37, 0, v37
	v_and_b32_e32 v38, 0x3ffff8f, v36
	v_lshlrev_b32_e32 v39, 6, v36
	v_xor_b32_e32 v36, v36, v40
	v_xor_b32_e32 v27, v27, v37
	v_lshlrev_b32_e32 v36, 4, v36
	v_lshlrev_b32_e32 v27, 4, v27
	v_and_b32_e32 v41, 0x1000, v39
	v_and_b32_e32 v36, 48, v36
	v_and_b32_e32 v27, 48, v27
	v_and_b32_e32 v42, 0x3c0, v39
	v_and_b32_e32 v39, 0xffffe3c0, v39
	v_lshl_add_u32 v38, v38, 6, v166
	v_lshl_or_b32 v152, v26, 6, v36
	v_or_b32_e32 v26, v27, v41
	s_mov_b32 s21, -2
	s_mov_b32 s25, s13
	v_mov_b32_e32 v0, 0
	v_mov_b32_e32 v1, v153
	v_or3_b32 v168, v41, v42, v27
	v_add_u32_e32 v169, v27, v39
	v_add_u32_e32 v170, v27, v38
	v_add_u32_e32 v171, v26, v42
	v_lshl_add_u64 v[158:159], v[154:155], 0, s[14:15]
	v_lshl_add_u64 v[160:161], v[154:155], 0, s[16:17]
	v_lshl_add_u64 v[162:163], v[154:155], 0, s[18:19]
	v_lshl_add_u64 v[164:165], v[156:157], 0, s[14:15]
	v_mov_b32_e32 v26, v153
	v_mov_b32_e32 v27, v153
	v_mov_b32_e32 v28, 0
	v_mov_b32_e32 v29, v153
	v_mov_b32_e32 v30, v153
	v_mov_b32_e32 v31, v153
	v_mov_b32_e32 v32, 0
	v_mov_b32_e32 v33, v153
	v_mov_b32_e32 v34, v153
	v_mov_b32_e32 v35, v153
	v_mov_b32_e32 v36, 0
	v_mov_b32_e32 v37, v153
	v_mov_b32_e32 v38, v153
	v_mov_b32_e32 v39, v153
	v_mov_b32_e32 v40, 0
	v_mov_b32_e32 v41, v153
	v_mov_b32_e32 v42, v153
	v_mov_b32_e32 v43, v153
	v_mov_b32_e32 v44, 0
	s_waitcnt vmcnt(11)
	ds_write_b128 v152, v[2:5]
	s_waitcnt vmcnt(10)
	ds_write_b128 v152, v[6:9] offset:4096
	s_waitcnt vmcnt(9)
	ds_write_b128 v152, v[10:13] offset:8192
	s_waitcnt vmcnt(8)
	ds_write_b128 v152, v[14:17] offset:12288
	s_waitcnt vmcnt(7)
	ds_write_b128 v152, v[18:21] offset:32768
	s_waitcnt vmcnt(6)
	ds_write_b128 v152, v[22:25] offset:36864
	v_mov_b32_e32 v2, v153
	v_mov_b32_e32 v3, v153
	v_mov_b32_e32 v4, 0
	v_mov_b32_e32 v5, v153
	v_mov_b32_e32 v6, v153
	v_mov_b32_e32 v7, v153
	v_mov_b32_e32 v8, 0
	v_mov_b32_e32 v9, v153
	v_mov_b32_e32 v10, v153
	v_mov_b32_e32 v11, v153
	v_mov_b32_e32 v12, 0
	v_mov_b32_e32 v13, v153
	v_mov_b32_e32 v14, v153
	v_mov_b32_e32 v15, v153
	v_mov_b32_e32 v16, 0
	v_mov_b32_e32 v17, v153
	v_mov_b32_e32 v18, v153
	v_mov_b32_e32 v19, v153
	v_mov_b32_e32 v20, 0
	v_mov_b32_e32 v21, v153
	v_mov_b32_e32 v22, v153
	v_mov_b32_e32 v23, v153
	v_mov_b32_e32 v24, 0
	v_mov_b32_e32 v25, v153
	v_mov_b32_e32 v45, v153
	v_mov_b32_e32 v46, v153
	v_mov_b32_e32 v47, v153
	v_mov_b32_e32 v48, 0
	v_mov_b32_e32 v49, v153
	v_mov_b32_e32 v50, v153
	v_mov_b32_e32 v51, v153
	v_mov_b32_e32 v52, 0
	v_mov_b32_e32 v53, v153
	v_mov_b32_e32 v54, v153
	v_mov_b32_e32 v55, v153
	v_mov_b32_e32 v56, 0
	v_mov_b32_e32 v57, v153
	v_mov_b32_e32 v58, v153
	v_mov_b32_e32 v59, v153
	v_mov_b32_e32 v60, 0
	v_mov_b32_e32 v61, v153
	v_mov_b32_e32 v62, v153
	v_mov_b32_e32 v63, v153
	v_mov_b32_e32 v64, 0
	v_mov_b32_e32 v65, v153
	v_mov_b32_e32 v66, v153
	v_mov_b32_e32 v67, v153
	v_mov_b32_e32 v68, 0
	v_mov_b32_e32 v69, v153
	v_mov_b32_e32 v70, v153
	v_mov_b32_e32 v71, v153
	v_mov_b32_e32 v72, 0
	v_mov_b32_e32 v73, v153
	v_mov_b32_e32 v74, v153
	v_mov_b32_e32 v75, v153
	v_mov_b32_e32 v76, 0
	v_mov_b32_e32 v77, v153
	v_mov_b32_e32 v78, v153
	v_mov_b32_e32 v79, v153
	v_mov_b32_e32 v80, 0
	v_mov_b32_e32 v81, v153
	v_mov_b32_e32 v82, v153
	v_mov_b32_e32 v83, v153
	v_mov_b32_e32 v84, 0
	v_mov_b32_e32 v85, v153
	v_mov_b32_e32 v86, v153
	v_mov_b32_e32 v87, v153
	v_mov_b32_e32 v88, 0
	v_mov_b32_e32 v89, v153
	v_mov_b32_e32 v90, v153
	v_mov_b32_e32 v91, v153
	v_mov_b32_e32 v92, 0
	v_mov_b32_e32 v93, v153
	v_mov_b32_e32 v94, v153
	v_mov_b32_e32 v95, v153
	v_mov_b32_e32 v96, 0
	v_mov_b32_e32 v97, v153
	v_mov_b32_e32 v98, v153
	v_mov_b32_e32 v99, v153
	v_mov_b32_e32 v100, 0
	v_mov_b32_e32 v101, v153
	v_mov_b32_e32 v102, v153
	v_mov_b32_e32 v103, v153
	v_mov_b32_e32 v104, 0
	v_mov_b32_e32 v105, v153
	v_mov_b32_e32 v106, v153
	v_mov_b32_e32 v107, v153
	v_mov_b32_e32 v108, 0
	v_mov_b32_e32 v109, v153
	v_mov_b32_e32 v110, v153
	v_mov_b32_e32 v111, v153
	v_mov_b32_e32 v112, 0
	v_mov_b32_e32 v113, v153
	v_mov_b32_e32 v114, v153
	v_mov_b32_e32 v115, v153
	v_mov_b32_e32 v116, 0
	v_mov_b32_e32 v117, v153
	v_mov_b32_e32 v118, v153
	v_mov_b32_e32 v119, v153
	v_mov_b32_e32 v144, 0
	v_mov_b32_e32 v145, v153
	v_mov_b32_e32 v146, v153
	v_mov_b32_e32 v147, v153
	v_mov_b32_e32 v148, 0
	v_mov_b32_e32 v149, v153
	v_mov_b32_e32 v150, v153
	v_mov_b32_e32 v151, v153
	s_waitcnt lgkmcnt(0)
	s_add_i32 s26, s25, 64
	s_min_u32 s12, s26, 0x3e0
	s_lshl_b32 s12, s12, 1
	v_lshl_add_u64 v[172:173], v[154:155], 0, s[12:13]
	v_lshl_add_u64 v[176:177], v[158:159], 0, s[12:13]
	v_lshl_add_u64 v[180:181], v[160:161], 0, s[12:13]
	v_lshl_add_u64 v[184:185], v[162:163], 0, s[12:13]
	v_lshl_add_u64 v[188:189], v[156:157], 0, s[12:13]
	v_lshl_add_u64 v[192:193], v[164:165], 0, s[12:13]
